# v48: P6 inter-chunk product keeps three q~ fragment reads in flight (third buffer v[200:203]), no per-group lgkmcnt(0)
# baseline (speedup 1.0000x reference)
; #define LAS __attribute__((address_space(3)))
; __device__ __forceinline__ unsigned cvtpk(float lo, float hi) { f32x2_t v = {lo, hi}; bf16x2_t b = __builtin_convertvector(v, bf16x2_t); return __builtin_bit_cast(unsigned, b); }
; template <class T> __device__ __forceinline__ LAS T* opq(LAS T* p) { unsigned a = __builtin_bit_cast(unsigned, p); asm volatile("" : "+v"(a)); return __builtin_bit_cast(LAS T*, a); }
; #define MFMA32(a, b, c) __builtin_amdgcn_mfma_f32_32x32x16_bf16((a), (b), (c), 0, 0, 0)
; template <bool FULL, bool PARTIAL  > ...
;     ...
;             const LAS bf16_t* qt_r4 = opq(QS + r * QST + 4 * h);
; #pragma unroll
;             for (int tb = 0; tb < 2; ++tb) oT[tb] = (f32x16){0.f, 0.f, 0.f, 0.f, 0.f, 0.f, 0.f, 0.f, 0.f, 0.f, 0.f, 0.f, 0.f, 0.f, 0.f, 0.f};
; #pragma unroll
;             for (int kb = 0; kb < 4; ++kb) {
; #pragma unroll
;                 for (int s2 = 0; s2 < 2; ++s2) {
;                     u32x4 sw; sw.x = cvtpk(Sacc[kb][8 * s2 + 0], Sacc[kb][8 * s2 + 1]); sw.y = cvtpk(Sacc[kb][8 * s2 + 2], Sacc[kb][8 * s2 + 3]);
;                     sw.z = cvtpk(Sacc[kb][8 * s2 + 4], Sacc[kb][8 * s2 + 5]); sw.w = cvtpk(Sacc[kb][8 * s2 + 6], Sacc[kb][8 * s2 + 7]);
;                     const bf16x8 sb = __builtin_bit_cast(bf16x8, sw);
; #pragma unroll
;                     for (int tb = 0; tb < 2; ++tb) {
;                         const LAS bf16_t* qp = qt_r4 + (32 * tb) * QST + 32 * kb + 16 * s2;
;                         const s16x4 lo = *(const LAS s16x4*)qp, hi = *(const LAS s16x4*)(qp + 8);
;                         const bf16x8 qa = __builtin_shufflevector(lo, hi, 0, 1, 2, 3, 4, 5, 6, 7);
;                         oT[tb] = MFMA32(sb, qa, oT[tb]);
;                     }
;                 }
;                 __builtin_amdgcn_sched_barrier(0);
;             }
;             __syncthreads();
.LBB0_1324:
	v_mov_b32_e32 v2, v225
	v_cvt_pk_bf16_f32 v4, v18, v19
	v_cvt_pk_bf16_f32 v5, v20, v21
	v_cvt_pk_bf16_f32 v6, v22, v23
	v_cvt_pk_bf16_f32 v7, v24, v25
	v_add_u32_e32 v150, 0x2000, v2
	ds_read2_b64 v[8:11], v2 offset1:2
	ds_read2_b64 v[12:15], v150 offset0:64 offset1:66
	ds_read2_b64 v[200:203], v2 offset0:4 offset1:6
	s_waitcnt lgkmcnt(2)
	v_mfma_f32_32x32x16_bf16 v[114:129], v[4:7], v[8:11], 0
	ds_read2_b64 v[8:11], v150 offset0:68 offset1:70
	s_waitcnt lgkmcnt(2)
	v_mfma_f32_32x32x16_bf16 v[98:113], v[4:7], v[12:15], 0
	ds_read2_b64 v[12:15], v2 offset0:8 offset1:10
	v_cvt_pk_bf16_f32 v4, v26, v27
	v_cvt_pk_bf16_f32 v5, v28, v29
	v_cvt_pk_bf16_f32 v6, v30, v31
	v_cvt_pk_bf16_f32 v7, v32, v33
	s_waitcnt lgkmcnt(2)
	v_mfma_f32_32x32x16_bf16 v[114:129], v[4:7], v[200:203], v[114:129]
	ds_read2_b64 v[200:203], v150 offset0:72 offset1:74
	s_waitcnt lgkmcnt(2)
	v_mfma_f32_32x32x16_bf16 v[98:113], v[4:7], v[8:11], v[98:113]
	ds_read2_b64 v[8:11], v2 offset0:12 offset1:14
	v_cvt_pk_bf16_f32 v4, v34, v35
	v_cvt_pk_bf16_f32 v5, v36, v37
	v_cvt_pk_bf16_f32 v6, v38, v39
	v_cvt_pk_bf16_f32 v7, v40, v41
	s_waitcnt lgkmcnt(2)
	v_mfma_f32_32x32x16_bf16 v[114:129], v[4:7], v[12:15], v[114:129]
	ds_read2_b64 v[12:15], v150 offset0:76 offset1:78
	s_waitcnt lgkmcnt(2)
	v_mfma_f32_32x32x16_bf16 v[98:113], v[4:7], v[200:203], v[98:113]
	ds_read2_b64 v[200:203], v2 offset0:16 offset1:18
	v_cvt_pk_bf16_f32 v4, v42, v43
	v_cvt_pk_bf16_f32 v5, v44, v45
	v_cvt_pk_bf16_f32 v6, v46, v47
	v_cvt_pk_bf16_f32 v7, v48, v49
	s_waitcnt lgkmcnt(2)
	v_mfma_f32_32x32x16_bf16 v[114:129], v[4:7], v[8:11], v[114:129]
	ds_read2_b64 v[8:11], v150 offset0:80 offset1:82
	s_waitcnt lgkmcnt(2)
	v_mfma_f32_32x32x16_bf16 v[98:113], v[4:7], v[12:15], v[98:113]
	ds_read2_b64 v[12:15], v2 offset0:20 offset1:22
	v_cvt_pk_bf16_f32 v4, v50, v51
	v_cvt_pk_bf16_f32 v5, v52, v53
	v_cvt_pk_bf16_f32 v6, v54, v55
	v_cvt_pk_bf16_f32 v7, v56, v57
	s_waitcnt lgkmcnt(2)
	v_mfma_f32_32x32x16_bf16 v[114:129], v[4:7], v[200:203], v[114:129]
	ds_read2_b64 v[200:203], v150 offset0:84 offset1:86
	s_waitcnt lgkmcnt(2)
	v_mfma_f32_32x32x16_bf16 v[98:113], v[4:7], v[8:11], v[98:113]
	ds_read2_b64 v[8:11], v2 offset0:24 offset1:26
	v_cvt_pk_bf16_f32 v4, v58, v59
	v_cvt_pk_bf16_f32 v5, v60, v61
	v_cvt_pk_bf16_f32 v6, v62, v63
	v_cvt_pk_bf16_f32 v7, v64, v65
	s_waitcnt lgkmcnt(2)
	v_mfma_f32_32x32x16_bf16 v[114:129], v[4:7], v[12:15], v[114:129]
	ds_read2_b64 v[12:15], v150 offset0:88 offset1:90
	s_waitcnt lgkmcnt(2)
	v_mfma_f32_32x32x16_bf16 v[98:113], v[4:7], v[200:203], v[98:113]
	ds_read2_b64 v[200:203], v2 offset0:28 offset1:30
	v_cvt_pk_bf16_f32 v4, v66, v67
	v_cvt_pk_bf16_f32 v5, v68, v69
	v_cvt_pk_bf16_f32 v6, v70, v71
	v_cvt_pk_bf16_f32 v7, v72, v73
	s_waitcnt lgkmcnt(2)
	v_mfma_f32_32x32x16_bf16 v[114:129], v[4:7], v[8:11], v[114:129]
	ds_read2_b64 v[8:11], v150 offset0:92 offset1:94
	s_waitcnt lgkmcnt(2)
	v_mfma_f32_32x32x16_bf16 v[98:113], v[4:7], v[12:15], v[98:113]
	v_cvt_pk_bf16_f32 v4, v74, v75
	v_cvt_pk_bf16_f32 v5, v76, v77
	v_cvt_pk_bf16_f32 v6, v78, v79
	v_cvt_pk_bf16_f32 v7, v80, v81
	s_waitcnt lgkmcnt(1)
	v_mfma_f32_32x32x16_bf16 v[114:129], v[4:7], v[200:203], v[114:129]
	s_waitcnt lgkmcnt(0)
	v_mfma_f32_32x32x16_bf16 v[98:113], v[4:7], v[8:11], v[98:113]
	v_lshl_add_u64 v[156:157], v[178:179], 0, s[60:61]
	s_mov_b32 s72, 0xa800000
	v_add_co_u32_e32 v158, vcc, s72, v156
	s_mov_b32 s72, 0xa820000
	s_nop 0
	v_addc_co_u32_e32 v159, vcc, 0, v157, vcc
	v_mov_b32_e32 v2, v245
	v_add_co_u32_e32 v156, vcc, s72, v156
	s_barrier
; template <bool FULL, bool PARTIAL  > ...
;     ...
;                 const LAS bf16_t* vt_r = opq(VS + (8 * h + ((lane & 15) >> 2)) * VST + 32 * w + 16 * ((lane >> 4) & 1) + 4 * (lane & 3));
; #pragma unroll
;                 for (int s4 = 0; s4 < 4; ++s4) { const s16x4 vlo = tr16(vt_r + (16 * s4) * VST), vhi = tr16(vt_r + (16 * s4 + 4) * VST); vfr[s4] = __builtin_shufflevector(vlo, vhi, 0, 1, 2, 3, 4, 5, 6, 7); }
;             }
; #pragma unroll
;             for (int tb = 0; tb < 2; ++tb)
; #pragma unroll
;                 for (int q4 = 0; q4 < 4; ++q4) grv[tb][q4] = *(const u32x2*)(AB + (size_t)crow0 * 2048 + hd * 256 + 32 * w + 8 * q4 + (unsigned)(min(32 * tb + r, nv1) * 2048 + 4 * h));
;             const LAS bf16_t* ab_r = opq(Ab + r * TST + 8 * h);
; #pragma unroll
;             for (int tb = 0; tb < 2; ++tb)
; #pragma unroll
;                 for (int sb = 0; sb < 2; ++sb) {
;                     if (sb > tb) continue;
; #pragma unroll
;                     for (int s2 = 0; s2 < 2; ++s2) {
;                         const bf16x8 aa = *(const LAS bf16x8*)(ab_r + (32 * tb) * TST + 32 * sb + 16 * s2);
;                         oT[tb] = MFMA32(vfr[2 * sb + s2], aa, oT[tb]);
;                     }
;                 }
;         }
;         const LAS bf16_t* kdt_r = opq(KdT + r * TST + 8 * h);
;         if (!FULL) {
;             const LAS bf16_t* vt_r2 = opq(VS + (8 * h + ((lane & 15) >> 2)) * VST + 32 * w + 16 * ((lane >> 4) & 1) + 4 * (lane & 3));
; #pragma unroll
;             for (int s4 = 0; s4 < 4; ++s4) { const s16x4 vlo = tr16(vt_r2 + (16 * s4) * VST), vhi = tr16(vt_r2 + (16 * s4 + 4) * VST); vfr[s4] = __builtin_shufflevector(vlo, vhi, 0, 1, 2, 3, 4, 5, 6, 7); }
;         }
;         const LAS float* eb_r = opq(EB + 4 * h);
; #pragma unroll
;         for (int kb = 0; kb < 4; ++kb) {
; #pragma unroll
;             for (int q4 = 0; q4 < 4; ++q4) { const f32x4 e = *(const LAS f32x4*)(eb_r + 32 * kb + 8 * q4);
; #pragma unroll
;                 for (int e2 = 0; e2 < 4; ++e2) Sacc[kb][4 * q4 + e2] *= e[e2]; }
; #pragma unroll
;             for (int s = 0; s < 4; ++s) {
;                 const bf16x8 ka = *(const LAS bf16x8*)(kdt_r + (32 * kb) * TST + 16 * s);
;                 Sacc[kb] = MFMA32(ka, vfr[s], Sacc[kb]);
;             }
;             __builtin_amdgcn_sched_barrier(0);
;         }
;         if (FULL) {
; #pragma unroll
	s_nop 0
	v_addc_co_u32_e32 v157, vcc, 0, v157, vcc
	ds_read_b64_tr_b16 v[4:5], v2
	ds_read_b64_tr_b16 v[6:7], v2 offset:2304
	ds_read_b64_tr_b16 v[12:13], v2 offset:9216
	ds_read_b64_tr_b16 v[14:15], v2 offset:11520
	ds_read_b64_tr_b16 v[150:151], v2 offset:18432
	ds_read_b64_tr_b16 v[152:153], v2 offset:20736
	ds_read_b64_tr_b16 v[8:9], v2 offset:27648
	ds_read_b64_tr_b16 v[10:11], v2 offset:29952
	global_load_dwordx2 v[194:195], v[158:159], off
	global_load_dwordx2 v[192:193], v[158:159], off offset:16
	global_load_dwordx2 v[190:191], v[158:159], off offset:32
	global_load_dwordx2 v[188:189], v[158:159], off offset:48
	global_load_dwordx2 v[186:187], v[156:157], off
	global_load_dwordx2 v[184:185], v[156:157], off offset:16
	global_load_dwordx2 v[182:183], v[156:157], off offset:32
	global_load_dwordx2 v[180:181], v[156:157], off offset:48
	v_mov_b32_e32 v2, v227
	ds_read_b128 v[156:159], v2
	ds_read_b128 v[200:203], v2 offset:32
	s_waitcnt lgkmcnt(1)
	v_mfma_f32_32x32x16_bf16 v[114:129], v[4:7], v[156:159], v[114:129]
	ds_read_b128 v[156:159], v2 offset:4608
	v_mov_b32_e32 v155, v229
	s_waitcnt lgkmcnt(0)
	v_mfma_f32_32x32x16_bf16 v[98:113], v[4:7], v[156:159], v[98:113]
	ds_read_b128 v[156:159], v2 offset:4640
	s_waitcnt lgkmcnt(0)
	v_mfma_f32_32x32x16_bf16 v[98:113], v[12:15], v[156:159], v[98:113]
	ds_read_b128 v[156:159], v2 offset:4672
	s_waitcnt lgkmcnt(0)
	v_mfma_f32_32x32x16_bf16 v[98:113], v[150:153], v[156:159], v[98:113]
	ds_read_b128 v[156:159], v2 offset:4704
	v_mov_b32_e32 v2, v228
	v_mfma_f32_32x32x16_bf16 v[114:129], v[12:15], v[200:203], v[114:129]
	s_waitcnt lgkmcnt(0)
	v_mfma_f32_32x32x16_bf16 v[98:113], v[8:11], v[156:159], v[98:113]
	ds_read_b128 v[156:159], v155
	ds_read_b128 v[200:203], v155 offset:32
	ds_read_b128 v[204:207], v155 offset:64
	ds_read_b128 v[208:211], v155 offset:96
	s_waitcnt lgkmcnt(3)
	v_pk_mul_f32 v[20:21], v[20:21], v[158:159]
	s_waitcnt lgkmcnt(2)
	v_pk_mul_f32 v[24:25], v[24:25], v[202:203]
	v_pk_mul_f32 v[22:23], v[22:23], v[200:201]
	v_pk_mul_f32 v[18:19], v[18:19], v[156:157]
	ds_read_b128 v[156:159], v2
	ds_read_b128 v[200:203], v2 offset:32
	s_waitcnt lgkmcnt(2)
	v_pk_mul_f32 v[32:33], v[32:33], v[210:211]
	v_pk_mul_f32 v[28:29], v[28:29], v[206:207]
	v_pk_mul_f32 v[30:31], v[30:31], v[208:209]
	v_pk_mul_f32 v[26:27], v[26:27], v[204:205]
	s_waitcnt lgkmcnt(1)
	s_nop 0
	v_mfma_f32_32x32x16_bf16 v[18:33], v[156:159], v[4:7], v[18:33]
	ds_read_b128 v[156:159], v2 offset:64
	s_waitcnt lgkmcnt(1)
	v_mfma_f32_32x32x16_bf16 v[18:33], v[200:203], v[12:15], v[18:33]
	s_waitcnt lgkmcnt(0)
	v_mfma_f32_32x32x16_bf16 v[18:33], v[156:159], v[150:153], v[18:33]
	ds_read_b128 v[156:159], v2 offset:96
	s_waitcnt lgkmcnt(0)
	v_mfma_f32_32x32x16_bf16 v[18:33], v[156:159], v[8:11], v[18:33]
	ds_read_b128 v[156:159], v155 offset:128
	ds_read_b128 v[200:203], v155 offset:160
	ds_read_b128 v[204:207], v155 offset:192
	ds_read_b128 v[208:211], v155 offset:224
	s_waitcnt lgkmcnt(3)
	v_pk_mul_f32 v[36:37], v[36:37], v[158:159]
	s_waitcnt lgkmcnt(2)
	v_pk_mul_f32 v[40:41], v[40:41], v[202:203]
	v_pk_mul_f32 v[38:39], v[38:39], v[200:201]
	v_pk_mul_f32 v[34:35], v[34:35], v[156:157]
	ds_read_b128 v[156:159], v2 offset:4608
	ds_read_b128 v[200:203], v2 offset:4640
	s_waitcnt lgkmcnt(2)
	v_pk_mul_f32 v[48:49], v[48:49], v[210:211]
	v_pk_mul_f32 v[44:45], v[44:45], v[206:207]
	v_pk_mul_f32 v[46:47], v[46:47], v[208:209]
	v_pk_mul_f32 v[42:43], v[42:43], v[204:205]
	s_waitcnt lgkmcnt(1)
	s_nop 0
	v_mfma_f32_32x32x16_bf16 v[34:49], v[156:159], v[4:7], v[34:49]
	ds_read_b128 v[156:159], v2 offset:4672
	s_waitcnt lgkmcnt(1)
	v_mfma_f32_32x32x16_bf16 v[34:49], v[200:203], v[12:15], v[34:49]
	s_waitcnt lgkmcnt(0)
	v_mfma_f32_32x32x16_bf16 v[34:49], v[156:159], v[150:153], v[34:49]
	ds_read_b128 v[156:159], v2 offset:4704
	s_waitcnt lgkmcnt(0)
	v_mfma_f32_32x32x16_bf16 v[34:49], v[156:159], v[8:11], v[34:49]
	ds_read_b128 v[156:159], v155 offset:256
	ds_read_b128 v[200:203], v155 offset:288
	ds_read_b128 v[204:207], v155 offset:320
	ds_read_b128 v[208:211], v155 offset:352
	s_waitcnt lgkmcnt(3)
	v_pk_mul_f32 v[52:53], v[52:53], v[158:159]
	s_waitcnt lgkmcnt(2)
	v_pk_mul_f32 v[56:57], v[56:57], v[202:203]
	v_pk_mul_f32 v[54:55], v[54:55], v[200:201]
	v_pk_mul_f32 v[50:51], v[50:51], v[156:157]
	ds_read_b128 v[156:159], v2 offset:9216
	ds_read_b128 v[200:203], v2 offset:9248
	s_waitcnt lgkmcnt(2)
	v_pk_mul_f32 v[64:65], v[64:65], v[210:211]
	v_pk_mul_f32 v[60:61], v[60:61], v[206:207]
	v_pk_mul_f32 v[62:63], v[62:63], v[208:209]
	v_pk_mul_f32 v[58:59], v[58:59], v[204:205]
	s_waitcnt lgkmcnt(1)
	s_nop 0
	v_mfma_f32_32x32x16_bf16 v[50:65], v[156:159], v[4:7], v[50:65]
	ds_read_b128 v[156:159], v2 offset:9280
	s_waitcnt lgkmcnt(1)
	v_mfma_f32_32x32x16_bf16 v[50:65], v[200:203], v[12:15], v[50:65]
	s_waitcnt lgkmcnt(0)
	v_mfma_f32_32x32x16_bf16 v[50:65], v[156:159], v[150:153], v[50:65]
	ds_read_b128 v[156:159], v2 offset:9312
	s_waitcnt lgkmcnt(0)
	v_mfma_f32_32x32x16_bf16 v[50:65], v[156:159], v[8:11], v[50:65]
	ds_read_b128 v[156:159], v155 offset:384
	ds_read_b128 v[200:203], v155 offset:416
	ds_read_b128 v[204:207], v155 offset:448
	ds_read_b128 v[208:211], v155 offset:480
	s_waitcnt lgkmcnt(3)
	v_pk_mul_f32 v[68:69], v[68:69], v[158:159]
	s_waitcnt lgkmcnt(2)
	v_pk_mul_f32 v[72:73], v[72:73], v[202:203]
	v_pk_mul_f32 v[70:71], v[70:71], v[200:201]
	v_pk_mul_f32 v[66:67], v[66:67], v[156:157]
	ds_read_b128 v[156:159], v2 offset:13824
	ds_read_b128 v[200:203], v2 offset:13856
	s_waitcnt lgkmcnt(2)
	v_pk_mul_f32 v[80:81], v[80:81], v[210:211]
	v_pk_mul_f32 v[76:77], v[76:77], v[206:207]
	v_pk_mul_f32 v[78:79], v[78:79], v[208:209]
	v_pk_mul_f32 v[74:75], v[74:75], v[204:205]
	s_waitcnt lgkmcnt(1)
	s_nop 0
	v_mfma_f32_32x32x16_bf16 v[66:81], v[156:159], v[4:7], v[66:81]
	ds_read_b128 v[4:7], v2 offset:13888
	s_waitcnt lgkmcnt(1)
	v_mfma_f32_32x32x16_bf16 v[66:81], v[200:203], v[12:15], v[66:81]
	s_waitcnt lgkmcnt(0)
	v_mfma_f32_32x32x16_bf16 v[66:81], v[4:7], v[150:153], v[66:81]
	ds_read_b128 v[4:7], v2 offset:13920
	s_waitcnt lgkmcnt(0)
	v_mfma_f32_32x32x16_bf16 v[66:81], v[4:7], v[8:11], v[66:81]
	v_mul_f32_e32 v2, v115, v115
	v_fmac_f32_e32 v2, v114, v114
	v_fmac_f32_e32 v2, v116, v116
	v_fmac_f32_e32 v2, v117, v117
	v_fmac_f32_e32 v2, v118, v118
	v_fmac_f32_e32 v2, v119, v119
	v_fmac_f32_e32 v2, v120, v120
	v_fmac_f32_e32 v2, v121, v121
	v_fmac_f32_e32 v2, v122, v122
	v_fmac_f32_e32 v2, v123, v123
	v_fmac_f32_e32 v2, v124, v124
	v_fmac_f32_e32 v2, v125, v125
	v_fmac_f32_e32 v2, v126, v126
	v_fmac_f32_e32 v2, v127, v127
	v_fmac_f32_e32 v2, v128, v128
	v_fmac_f32_e32 v2, v129, v129
	v_mov_b32_e32 v4, v2
	s_nop 1
	v_permlane32_swap_b32_e32 v2, v4
	s_and_saveexec_b64 s[72:73], s[4:5]
	s_cbranch_execz .LBB0_1326
	s_waitcnt lgkmcnt(0)
	v_add_f32_e32 v2, v2, v4
	ds_write_b32 v246, v2
